# write-through publish after every second round (and the last)
# speedup vs baseline: 1.0003x; 1.0003x over previous
; DEVINL void rw_project_head(const Ctx& c, int layer, int b, int hd, int pj, int nP, unsigned* cnt, unsigned char* lds) {
;     ...
;         asm volatile("s_waitcnt vmcnt(0)" ::: "memory");
;         __syncthreads();
;         if (threadIdx.x == 0) {
;             __builtin_amdgcn_fence(__ATOMIC_RELEASE, "agent");
;             __hip_atomic_store(cnt, (unsigned)(layer * 16 + round + 1), __ATOMIC_RELAXED, __HIP_MEMORY_SCOPE_AGENT);
;         }
.LBB0_237:
	s_or_b64 exec, exec, s[12:13]
	s_waitcnt vmcnt(0)
	s_waitcnt vmcnt(63) expcnt(7) lgkmcnt(15)
	s_barrier
	s_mov_b64 s[0:1], exec
	v_cmp_eq_u32_e32 vcc, 0x1c0, v160
	s_nop 0
	s_and_b64 s[12:13], s[0:1], vcc
	s_mov_b64 exec, s[12:13]
	s_cbranch_execz .LBB0_140
	s_add_i32 s12, s16, s20
	s_cmp_lt_u32 s12, s17
	s_cbranch_scc0 .Lpub_do
	s_sub_i32 s13, s19, 1
	s_and_b32 s13, s13, 15
	s_movk_i32 s12, 0x2aa
	s_movk_i32 s14, 0x2a
	s_cmp_eq_u32 s30, 3
	s_cselect_b32 s12, s14, s12
	s_bitcmp1_b32 s12, s13
	s_cbranch_scc0 .LBB0_140
